# all GEMM K-loops placed so MFMA bursts sit at the same 64-byte-line offsets as the input-projection loop (heads at 16 / 56 mod 64)
# speedup vs baseline: 1.0428x; 1.0428x over previous
; template <class Epi, class Sched, bool ALIGN_EPI = false, bool SP2 = false>
; __device__ __forceinline__ void gemm_phase(PG8_LAS unsigned char* lds, const Gemm g, const Sched& S, const Epi& E, const int tid_arg) {
;     ...
;         const bool has_next = S.next(ui + 1, nxt);
;         const char* nA = has_next ? (const char*)g.A + (size_t)nxt.pm * tstep : cA; const char* nB = has_next ? (const char*)g.Bt + (size_t)nxt.pn * tstep : cB;
;     ...
; #pragma unroll
;         for (int a = 0; a < 2; ++a)
; #pragma unroll
;             for (int b = 0; b < 2; ++b)
; #pragma unroll
;                 for (int m = 0; m < 4; ++m)
; #pragma unroll
;                     for (int n = 0; n < 2; ++n) acc[a][b][m][n] = (f32x4){0.f, 0.f, 0.f, 0.f};
;         cur = nxt; cA = nA; cB = nB; ++ui;
.LBB0_95:
	s_ashr_i32 s21, s20, 31
	s_lshl_b64 s[22:23], s[20:21], 19
	s_add_u32 s22, s1, s22
	s_addc_u32 s23, s2, s23
	s_and_b64 s[24:25], s[6:7], exec
	s_cselect_b32 s21, s23, s29
	s_cselect_b32 s45, s22, s28
	s_ashr_i32 s19, s18, 31
	s_lshl_b64 s[24:25], s[18:19], 19
	s_add_u32 s24, s12, s24
	s_addc_u32 s25, s13, s25
	s_and_b64 s[34:35], s[6:7], exec
	s_cselect_b32 s19, s25, s31
	s_cselect_b32 s46, s24, s30
	s_add_u32 s28, s28, 0x40080
	s_addc_u32 s29, s29, 0
	s_add_u32 s47, s30, 0x100
	v_mov_b32_e32 v2, 0
	s_addc_u32 s48, s31, 0
	s_mov_b32 s49, -2
	v_mov_b32_e32 v3, v2
	v_mov_b32_e32 v4, v2
	v_mov_b32_e32 v5, v2
	v_mov_b32_e32 v6, v2
	v_mov_b32_e32 v7, v2
	v_mov_b32_e32 v8, v2
	v_mov_b32_e32 v9, v2
	v_mov_b32_e32 v18, v2
	v_mov_b32_e32 v19, v2
	v_mov_b32_e32 v20, v2
	v_mov_b32_e32 v21, v2
	v_mov_b32_e32 v22, v2
	v_mov_b32_e32 v23, v2
	v_mov_b32_e32 v24, v2
	v_mov_b32_e32 v25, v2
	v_mov_b32_e32 v34, v2
	v_mov_b32_e32 v35, v2
	v_mov_b32_e32 v36, v2
	v_mov_b32_e32 v37, v2
	v_mov_b32_e32 v38, v2
	v_mov_b32_e32 v39, v2
	v_mov_b32_e32 v40, v2
	v_mov_b32_e32 v41, v2
	v_mov_b32_e32 v50, v2
	v_mov_b32_e32 v51, v2
	v_mov_b32_e32 v52, v2
	v_mov_b32_e32 v53, v2
	v_mov_b32_e32 v54, v2
	v_mov_b32_e32 v55, v2
	v_mov_b32_e32 v56, v2
	v_mov_b32_e32 v57, v2
	v_mov_b32_e32 v10, v2
	v_mov_b32_e32 v11, v2
	v_mov_b32_e32 v12, v2
	v_mov_b32_e32 v13, v2
	v_mov_b32_e32 v14, v2
	v_mov_b32_e32 v15, v2
	v_mov_b32_e32 v16, v2
	v_mov_b32_e32 v17, v2
	v_mov_b32_e32 v26, v2
	v_mov_b32_e32 v27, v2
	v_mov_b32_e32 v28, v2
	v_mov_b32_e32 v29, v2
	v_mov_b32_e32 v30, v2
	v_mov_b32_e32 v31, v2
	v_mov_b32_e32 v32, v2
	v_mov_b32_e32 v33, v2
	v_mov_b32_e32 v42, v2
	v_mov_b32_e32 v43, v2
	v_mov_b32_e32 v44, v2
	v_mov_b32_e32 v45, v2
	v_mov_b32_e32 v46, v2
	v_mov_b32_e32 v47, v2
	v_mov_b32_e32 v48, v2
	v_mov_b32_e32 v49, v2
	v_mov_b32_e32 v58, v2
	v_mov_b32_e32 v59, v2
	v_mov_b32_e32 v60, v2
	v_mov_b32_e32 v61, v2
	v_mov_b32_e32 v62, v2
	v_mov_b32_e32 v63, v2
	v_mov_b32_e32 v64, v2
	v_mov_b32_e32 v65, v2
	v_mov_b32_e32 v66, v2
	v_mov_b32_e32 v67, v2
	v_mov_b32_e32 v68, v2
	v_mov_b32_e32 v69, v2
	v_mov_b32_e32 v70, v2
	v_mov_b32_e32 v71, v2
	v_mov_b32_e32 v72, v2
	v_mov_b32_e32 v73, v2
	v_mov_b32_e32 v82, v2
	v_mov_b32_e32 v83, v2
	v_mov_b32_e32 v84, v2
	v_mov_b32_e32 v85, v2
	v_mov_b32_e32 v86, v2
	v_mov_b32_e32 v87, v2
	v_mov_b32_e32 v88, v2
	v_mov_b32_e32 v89, v2
	v_mov_b32_e32 v98, v2
	v_mov_b32_e32 v99, v2
	v_mov_b32_e32 v100, v2
	v_mov_b32_e32 v101, v2
	v_mov_b32_e32 v102, v2
	v_mov_b32_e32 v103, v2
	v_mov_b32_e32 v104, v2
	v_mov_b32_e32 v105, v2
	v_mov_b32_e32 v114, v2
	v_mov_b32_e32 v115, v2
	v_mov_b32_e32 v116, v2
	v_mov_b32_e32 v117, v2
	v_mov_b32_e32 v118, v2
	v_mov_b32_e32 v119, v2
	v_mov_b32_e32 v120, v2
	v_mov_b32_e32 v121, v2
	v_mov_b32_e32 v74, v2
	v_mov_b32_e32 v75, v2
	v_mov_b32_e32 v76, v2
	v_mov_b32_e32 v77, v2
	v_mov_b32_e32 v78, v2
	v_mov_b32_e32 v79, v2
	v_mov_b32_e32 v80, v2
	v_mov_b32_e32 v81, v2
	v_mov_b32_e32 v90, v2
	v_mov_b32_e32 v91, v2
	v_mov_b32_e32 v92, v2
	v_mov_b32_e32 v93, v2
	v_mov_b32_e32 v94, v2
	v_mov_b32_e32 v95, v2
	v_mov_b32_e32 v96, v2
	v_mov_b32_e32 v97, v2
	v_mov_b32_e32 v106, v2
	v_mov_b32_e32 v107, v2
	v_mov_b32_e32 v108, v2
	v_mov_b32_e32 v109, v2
	v_mov_b32_e32 v110, v2
	v_mov_b32_e32 v111, v2
	v_mov_b32_e32 v112, v2
	v_mov_b32_e32 v113, v2
	v_mov_b32_e32 v122, v2
	v_mov_b32_e32 v123, v2
	v_mov_b32_e32 v124, v2
	v_mov_b32_e32 v125, v2
	v_mov_b32_e32 v126, v2
	v_mov_b32_e32 v127, v2
	v_mov_b32_e32 v128, v2
	v_mov_b32_e32 v129, v2
	.p2align 6
	s_nop 0
	s_nop 0
	s_nop 0
	s_nop 0

; template <class Epi, class Sched, bool ALIGN_EPI = false, bool SP2 = false>
; __device__ __forceinline__ void gemm_phase(PG8_LAS unsigned char* lds, const Gemm g, const Sched& S, const Epi& E, const int tid_arg) {
;     ...
; #pragma unroll
;         for (int a = 0; a < 2; ++a)
; #pragma unroll
;             for (int b = 0; b < 2; ++b)
; #pragma unroll
;                 for (int m = 0; m < 4; ++m)
; #pragma unroll
;                     for (int n = 0; n < 2; ++n) acc[a][b][m][n] = (f32x4){0.f, 0.f, 0.f, 0.f};
;         cur = nxt; cA = nA; cB = nB; ++ui;
.LBB0_259:
	s_add_u32 s16, s36, 0x100
	v_mov_b32_e32 v2, 0
	s_addc_u32 s31, s37, 0
	s_mov_b32 s56, -2
	s_waitcnt lgkmcnt(0)
	v_mov_b32_e32 v3, v2
	v_mov_b32_e32 v4, v2
	v_mov_b32_e32 v5, v2
	v_mov_b32_e32 v6, v2
	v_mov_b32_e32 v7, v2
	v_mov_b32_e32 v8, v2
	v_mov_b32_e32 v9, v2
	v_mov_b32_e32 v18, v2
	v_mov_b32_e32 v19, v2
	v_mov_b32_e32 v20, v2
	v_mov_b32_e32 v21, v2
	v_mov_b32_e32 v22, v2
	v_mov_b32_e32 v23, v2
	v_mov_b32_e32 v24, v2
	v_mov_b32_e32 v25, v2
	v_mov_b32_e32 v34, v2
	v_mov_b32_e32 v35, v2
	v_mov_b32_e32 v36, v2
	v_mov_b32_e32 v37, v2
	v_mov_b32_e32 v38, v2
	v_mov_b32_e32 v39, v2
	v_mov_b32_e32 v40, v2
	v_mov_b32_e32 v41, v2
	v_mov_b32_e32 v50, v2
	v_mov_b32_e32 v51, v2
	v_mov_b32_e32 v52, v2
	v_mov_b32_e32 v53, v2
	v_mov_b32_e32 v54, v2
	v_mov_b32_e32 v55, v2
	v_mov_b32_e32 v56, v2
	v_mov_b32_e32 v57, v2
	v_mov_b32_e32 v10, v2
	v_mov_b32_e32 v11, v2
	v_mov_b32_e32 v12, v2
	v_mov_b32_e32 v13, v2
	v_mov_b32_e32 v14, v2
	v_mov_b32_e32 v15, v2
	v_mov_b32_e32 v16, v2
	v_mov_b32_e32 v17, v2
	v_mov_b32_e32 v26, v2
	v_mov_b32_e32 v27, v2
	v_mov_b32_e32 v28, v2
	v_mov_b32_e32 v29, v2
	v_mov_b32_e32 v30, v2
	v_mov_b32_e32 v31, v2
	v_mov_b32_e32 v32, v2
	v_mov_b32_e32 v33, v2
	v_mov_b32_e32 v42, v2
	v_mov_b32_e32 v43, v2
	v_mov_b32_e32 v44, v2
	v_mov_b32_e32 v45, v2
	v_mov_b32_e32 v46, v2
	v_mov_b32_e32 v47, v2
	v_mov_b32_e32 v48, v2
	v_mov_b32_e32 v49, v2
	v_mov_b32_e32 v58, v2
	v_mov_b32_e32 v59, v2
	v_mov_b32_e32 v60, v2
	v_mov_b32_e32 v61, v2
	v_mov_b32_e32 v62, v2
	v_mov_b32_e32 v63, v2
	v_mov_b32_e32 v64, v2
	v_mov_b32_e32 v65, v2
	v_mov_b32_e32 v66, v2
	v_mov_b32_e32 v67, v2
	v_mov_b32_e32 v68, v2
	v_mov_b32_e32 v69, v2
	v_mov_b32_e32 v70, v2
	v_mov_b32_e32 v71, v2
	v_mov_b32_e32 v72, v2
	v_mov_b32_e32 v73, v2
	v_mov_b32_e32 v82, v2
	v_mov_b32_e32 v83, v2
	v_mov_b32_e32 v84, v2
	v_mov_b32_e32 v85, v2
	v_mov_b32_e32 v86, v2
	v_mov_b32_e32 v87, v2
	v_mov_b32_e32 v88, v2
	v_mov_b32_e32 v89, v2
	v_mov_b32_e32 v98, v2
	v_mov_b32_e32 v99, v2
	v_mov_b32_e32 v100, v2
	v_mov_b32_e32 v101, v2
	v_mov_b32_e32 v102, v2
	v_mov_b32_e32 v103, v2
	v_mov_b32_e32 v104, v2
	v_mov_b32_e32 v105, v2
	v_mov_b32_e32 v114, v2
	v_mov_b32_e32 v115, v2
	v_mov_b32_e32 v116, v2
	v_mov_b32_e32 v117, v2
	v_mov_b32_e32 v118, v2
	v_mov_b32_e32 v119, v2
	v_mov_b32_e32 v120, v2
	v_mov_b32_e32 v121, v2
	v_mov_b32_e32 v74, v2
	v_mov_b32_e32 v75, v2
	v_mov_b32_e32 v76, v2
	v_mov_b32_e32 v77, v2
	v_mov_b32_e32 v78, v2
	v_mov_b32_e32 v79, v2
	v_mov_b32_e32 v80, v2
	v_mov_b32_e32 v81, v2
	v_mov_b32_e32 v90, v2
	v_mov_b32_e32 v91, v2
	v_mov_b32_e32 v92, v2
	v_mov_b32_e32 v93, v2
	v_mov_b32_e32 v94, v2
	v_mov_b32_e32 v95, v2
	v_mov_b32_e32 v96, v2
	v_mov_b32_e32 v97, v2
	v_mov_b32_e32 v106, v2
	v_mov_b32_e32 v107, v2
	v_mov_b32_e32 v108, v2
	v_mov_b32_e32 v109, v2
	v_mov_b32_e32 v110, v2
	v_mov_b32_e32 v111, v2
	v_mov_b32_e32 v112, v2
	v_mov_b32_e32 v113, v2
	v_mov_b32_e32 v122, v2
	v_mov_b32_e32 v123, v2
	v_mov_b32_e32 v124, v2
	v_mov_b32_e32 v125, v2
	v_mov_b32_e32 v126, v2
	v_mov_b32_e32 v127, v2
	v_mov_b32_e32 v128, v2
	v_mov_b32_e32 v129, v2
	.p2align 6
	s_nop 0
	s_nop 0
	s_nop 0
	s_nop 0

; template <class Epi, class Sched, bool ALIGN_EPI = false, bool SP2 = false>
; __device__ __forceinline__ void gemm_phase(PG8_LAS unsigned char* lds, const Gemm g, const Sched& S, const Epi& E, const int tid_arg) {
;     ...
;         const bool has_next = S.next(ui + 1, nxt);
;         const char* nA = has_next ? (const char*)g.A + (size_t)nxt.pm * tstep : cA; const char* nB = has_next ? (const char*)g.Bt + (size_t)nxt.pn * tstep : cB;
;     ...
; #pragma unroll
;         for (int a = 0; a < 2; ++a)
; #pragma unroll
;             for (int b = 0; b < 2; ++b)
; #pragma unroll
;                 for (int m = 0; m < 4; ++m)
; #pragma unroll
;                     for (int n = 0; n < 2; ++n) acc[a][b][m][n] = (f32x4){0.f, 0.f, 0.f, 0.f};
;         cur = nxt; cA = nA; cB = nB; ++ui;
.LBB0_362:
	s_ashr_i32 s29, s28, 31
	s_lshl_b64 s[6:7], s[28:29], 19
	s_add_u32 s30, s50, s6
	s_addc_u32 s31, s51, s7
	s_and_b64 s[6:7], s[8:9], exec
	s_cselect_b32 s6, s31, s15
	s_cselect_b32 s7, s30, s14
	s_ashr_i32 s27, s26, 31
	s_lshl_b64 s[34:35], s[26:27], 19
	s_add_u32 s34, s52, s34
	s_addc_u32 s35, s53, s35
	s_and_b64 s[38:39], s[8:9], exec
	s_cselect_b32 s11, s35, s37
	s_cselect_b32 s13, s34, s36
	s_add_u32 s14, s14, 0x40080
	s_addc_u32 s15, s15, 0
	s_add_u32 s27, s36, 0x100
	v_mov_b32_e32 v4, 0
	s_addc_u32 s29, s37, 0
	s_mov_b32 s40, -2
	v_mov_b32_e32 v5, v4
	v_mov_b32_e32 v6, v4
	v_mov_b32_e32 v7, v4
	v_mov_b32_e32 v8, v4
	v_mov_b32_e32 v9, v4
	v_mov_b32_e32 v10, v4
	v_mov_b32_e32 v11, v4
	v_mov_b32_e32 v20, v4
	v_mov_b32_e32 v21, v4
	v_mov_b32_e32 v22, v4
	v_mov_b32_e32 v23, v4
	v_mov_b32_e32 v24, v4
	v_mov_b32_e32 v25, v4
	v_mov_b32_e32 v26, v4
	v_mov_b32_e32 v27, v4
	v_mov_b32_e32 v36, v4
	v_mov_b32_e32 v37, v4
	v_mov_b32_e32 v38, v4
	v_mov_b32_e32 v39, v4
	v_mov_b32_e32 v40, v4
	v_mov_b32_e32 v41, v4
	v_mov_b32_e32 v42, v4
	v_mov_b32_e32 v43, v4
	v_mov_b32_e32 v52, v4
	v_mov_b32_e32 v53, v4
	v_mov_b32_e32 v54, v4
	v_mov_b32_e32 v55, v4
	v_mov_b32_e32 v56, v4
	v_mov_b32_e32 v57, v4
	v_mov_b32_e32 v58, v4
	v_mov_b32_e32 v59, v4
	v_mov_b32_e32 v12, v4
	v_mov_b32_e32 v13, v4
	v_mov_b32_e32 v14, v4
	v_mov_b32_e32 v15, v4
	v_mov_b32_e32 v16, v4
	v_mov_b32_e32 v17, v4
	v_mov_b32_e32 v18, v4
	v_mov_b32_e32 v19, v4
	v_mov_b32_e32 v28, v4
	v_mov_b32_e32 v29, v4
	v_mov_b32_e32 v30, v4
	v_mov_b32_e32 v31, v4
	v_mov_b32_e32 v32, v4
	v_mov_b32_e32 v33, v4
	v_mov_b32_e32 v34, v4
	v_mov_b32_e32 v35, v4
	v_mov_b32_e32 v44, v4
	v_mov_b32_e32 v45, v4
	v_mov_b32_e32 v46, v4
	v_mov_b32_e32 v47, v4
	v_mov_b32_e32 v48, v4
	v_mov_b32_e32 v49, v4
	v_mov_b32_e32 v50, v4
	v_mov_b32_e32 v51, v4
	v_mov_b32_e32 v60, v4
	v_mov_b32_e32 v61, v4
	v_mov_b32_e32 v62, v4
	v_mov_b32_e32 v63, v4
	v_mov_b32_e32 v64, v4
	v_mov_b32_e32 v65, v4
	v_mov_b32_e32 v66, v4
	v_mov_b32_e32 v67, v4
	v_mov_b32_e32 v68, v4
	v_mov_b32_e32 v69, v4
	v_mov_b32_e32 v70, v4
	v_mov_b32_e32 v71, v4
	v_mov_b32_e32 v72, v4
	v_mov_b32_e32 v73, v4
	v_mov_b32_e32 v74, v4
	v_mov_b32_e32 v75, v4
	v_mov_b32_e32 v84, v4
	v_mov_b32_e32 v85, v4
	v_mov_b32_e32 v86, v4
	v_mov_b32_e32 v87, v4
	v_mov_b32_e32 v88, v4
	v_mov_b32_e32 v89, v4
	v_mov_b32_e32 v90, v4
	v_mov_b32_e32 v91, v4
	v_mov_b32_e32 v100, v4
	v_mov_b32_e32 v101, v4
	v_mov_b32_e32 v102, v4
	v_mov_b32_e32 v103, v4
	v_mov_b32_e32 v104, v4
	v_mov_b32_e32 v105, v4
	v_mov_b32_e32 v106, v4
	v_mov_b32_e32 v107, v4
	v_mov_b32_e32 v116, v4
	v_mov_b32_e32 v117, v4
	v_mov_b32_e32 v118, v4
	v_mov_b32_e32 v119, v4
	s_waitcnt vmcnt(0)
	v_mov_b32_e32 v120, v4
	v_mov_b32_e32 v121, v4
	v_mov_b32_e32 v122, v4
	v_mov_b32_e32 v123, v4
	v_mov_b32_e32 v76, v4
	v_mov_b32_e32 v77, v4
	v_mov_b32_e32 v78, v4
	v_mov_b32_e32 v79, v4
	v_mov_b32_e32 v80, v4
	v_mov_b32_e32 v81, v4
	v_mov_b32_e32 v82, v4
	v_mov_b32_e32 v83, v4
	v_mov_b32_e32 v92, v4
	v_mov_b32_e32 v93, v4
	v_mov_b32_e32 v94, v4
	v_mov_b32_e32 v95, v4
	v_mov_b32_e32 v96, v4
	v_mov_b32_e32 v97, v4
	v_mov_b32_e32 v98, v4
	v_mov_b32_e32 v99, v4
	v_mov_b32_e32 v108, v4
	v_mov_b32_e32 v109, v4
	v_mov_b32_e32 v110, v4
	v_mov_b32_e32 v111, v4
	v_mov_b32_e32 v112, v4
	v_mov_b32_e32 v113, v4
	v_mov_b32_e32 v114, v4
	v_mov_b32_e32 v115, v4
	v_mov_b32_e32 v124, v4
	v_mov_b32_e32 v125, v4
	v_mov_b32_e32 v126, v4
	v_mov_b32_e32 v127, v4
	v_mov_b32_e32 v128, v4
	v_mov_b32_e32 v129, v4
	v_mov_b32_e32 v130, v4
	v_mov_b32_e32 v131, v4
	.p2align 6
	s_nop 0
	s_nop 0
	s_nop 0
	s_nop 0
	s_nop 0
	s_nop 0
	s_nop 0
	s_nop 0
	s_nop 0
	s_nop 0
	s_nop 0
	s_nop 0
	s_nop 0
	s_nop 0

; template <class Epi, class Sched, bool ALIGN_EPI = false, bool SP2 = false>
; __device__ __forceinline__ void gemm_phase(PG8_LAS unsigned char* lds, const Gemm g, const Sched& S, const Epi& E, const int tid_arg) {
;     ...
;         const bool has_next = S.next(ui + 1, nxt);
;         const char* nA = has_next ? (const char*)g.A + (size_t)nxt.pm * tstep : cA; const char* nB = has_next ? (const char*)g.Bt + (size_t)nxt.pn * tstep : cB;
;     ...
; #pragma unroll
;         for (int a = 0; a < 2; ++a)
; #pragma unroll
;             for (int b = 0; b < 2; ++b)
; #pragma unroll
;                 for (int m = 0; m < 4; ++m)
; #pragma unroll
;                     for (int n = 0; n < 2; ++n) acc[a][b][m][n] = (f32x4){0.f, 0.f, 0.f, 0.f};
;         cur = nxt; cA = nA; cB = nB; ++ui;
.LBB0_763:
	s_ashr_i32 s27, s26, 31
	s_lshl_b64 s[28:29], s[26:27], 19
	s_add_u32 s28, s3, s28
	s_addc_u32 s29, s6, s29
	s_and_b64 s[30:31], s[10:11], exec
	s_cselect_b32 s27, s29, s5
	s_cselect_b32 s48, s28, s4
	s_ashr_i32 s25, s24, 31
	s_lshl_b64 s[30:31], s[24:25], 19
	s_add_u32 s30, s7, s30
	s_addc_u32 s31, s38, s31
	s_and_b64 s[36:37], s[10:11], exec
	s_cselect_b32 s25, s31, s35
	s_cselect_b32 s49, s30, s34
	s_add_u32 s4, s4, 0x40080
	s_addc_u32 s5, s5, 0
	s_add_u32 s50, s34, 0x100
	v_mov_b32_e32 v4, 0
	s_addc_u32 s51, s35, 0
	s_mov_b32 s52, -2
	v_mov_b32_e32 v5, v4
	v_mov_b32_e32 v6, v4
	v_mov_b32_e32 v7, v4
	v_mov_b32_e32 v8, v4
	v_mov_b32_e32 v9, v4
	v_mov_b32_e32 v10, v4
	v_mov_b32_e32 v11, v4
	v_mov_b32_e32 v20, v4
	v_mov_b32_e32 v21, v4
	v_mov_b32_e32 v22, v4
	v_mov_b32_e32 v23, v4
	v_mov_b32_e32 v24, v4
	v_mov_b32_e32 v25, v4
	v_mov_b32_e32 v26, v4
	v_mov_b32_e32 v27, v4
	v_mov_b32_e32 v36, v4
	v_mov_b32_e32 v37, v4
	v_mov_b32_e32 v38, v4
	v_mov_b32_e32 v39, v4
	v_mov_b32_e32 v40, v4
	v_mov_b32_e32 v41, v4
	v_mov_b32_e32 v42, v4
	v_mov_b32_e32 v43, v4
	v_mov_b32_e32 v52, v4
	v_mov_b32_e32 v53, v4
	v_mov_b32_e32 v54, v4
	v_mov_b32_e32 v55, v4
	v_mov_b32_e32 v56, v4
	v_mov_b32_e32 v57, v4
	v_mov_b32_e32 v58, v4
	v_mov_b32_e32 v59, v4
	v_mov_b32_e32 v12, v4
	v_mov_b32_e32 v13, v4
	v_mov_b32_e32 v14, v4
	v_mov_b32_e32 v15, v4
	v_mov_b32_e32 v16, v4
	v_mov_b32_e32 v17, v4
	v_mov_b32_e32 v18, v4
	v_mov_b32_e32 v19, v4
	v_mov_b32_e32 v28, v4
	v_mov_b32_e32 v29, v4
	v_mov_b32_e32 v30, v4
	v_mov_b32_e32 v31, v4
	v_mov_b32_e32 v32, v4
	v_mov_b32_e32 v33, v4
	v_mov_b32_e32 v34, v4
	v_mov_b32_e32 v35, v4
	v_mov_b32_e32 v44, v4
	v_mov_b32_e32 v45, v4
	v_mov_b32_e32 v46, v4
	v_mov_b32_e32 v47, v4
	v_mov_b32_e32 v48, v4
	v_mov_b32_e32 v49, v4
	v_mov_b32_e32 v50, v4
	v_mov_b32_e32 v51, v4
	v_mov_b32_e32 v60, v4
	v_mov_b32_e32 v61, v4
	v_mov_b32_e32 v62, v4
	v_mov_b32_e32 v63, v4
	v_mov_b32_e32 v64, v4
	v_mov_b32_e32 v65, v4
	v_mov_b32_e32 v66, v4
	v_mov_b32_e32 v67, v4
	v_mov_b32_e32 v68, v4
	v_mov_b32_e32 v69, v4
	v_mov_b32_e32 v70, v4
	v_mov_b32_e32 v71, v4
	v_mov_b32_e32 v72, v4
	v_mov_b32_e32 v73, v4
	v_mov_b32_e32 v74, v4
	v_mov_b32_e32 v75, v4
	v_mov_b32_e32 v84, v4
	v_mov_b32_e32 v85, v4
	v_mov_b32_e32 v86, v4
	v_mov_b32_e32 v87, v4
	v_mov_b32_e32 v88, v4
	v_mov_b32_e32 v89, v4
	v_mov_b32_e32 v90, v4
	v_mov_b32_e32 v91, v4
	v_mov_b32_e32 v100, v4
	v_mov_b32_e32 v101, v4
	v_mov_b32_e32 v102, v4
	v_mov_b32_e32 v103, v4
	v_mov_b32_e32 v104, v4
	v_mov_b32_e32 v105, v4
	v_mov_b32_e32 v106, v4
	v_mov_b32_e32 v107, v4
	v_mov_b32_e32 v116, v4
	v_mov_b32_e32 v117, v4
	v_mov_b32_e32 v118, v4
	v_mov_b32_e32 v119, v4
	s_waitcnt vmcnt(0)
	v_mov_b32_e32 v120, v4
	v_mov_b32_e32 v121, v4
	v_mov_b32_e32 v122, v4
	v_mov_b32_e32 v123, v4
	v_mov_b32_e32 v76, v4
	v_mov_b32_e32 v77, v4
	v_mov_b32_e32 v78, v4
	v_mov_b32_e32 v79, v4
	v_mov_b32_e32 v80, v4
	v_mov_b32_e32 v81, v4
	v_mov_b32_e32 v82, v4
	v_mov_b32_e32 v83, v4
	v_mov_b32_e32 v92, v4
	v_mov_b32_e32 v93, v4
	v_mov_b32_e32 v94, v4
	v_mov_b32_e32 v95, v4
	v_mov_b32_e32 v96, v4
	v_mov_b32_e32 v97, v4
	v_mov_b32_e32 v98, v4
	v_mov_b32_e32 v99, v4
	v_mov_b32_e32 v108, v4
	v_mov_b32_e32 v109, v4
	v_mov_b32_e32 v110, v4
	v_mov_b32_e32 v111, v4
	v_mov_b32_e32 v112, v4
	v_mov_b32_e32 v113, v4
	v_mov_b32_e32 v114, v4
	v_mov_b32_e32 v115, v4
	v_mov_b32_e32 v124, v4
	v_mov_b32_e32 v125, v4
	v_mov_b32_e32 v126, v4
	v_mov_b32_e32 v127, v4
	v_mov_b32_e32 v128, v4
	v_mov_b32_e32 v129, v4
	v_mov_b32_e32 v130, v4
	v_mov_b32_e32 v131, v4
	.p2align 6
	s_nop 0
	s_nop 0
	s_nop 0
	s_nop 0
	s_nop 0
	s_nop 0
	s_nop 0
	s_nop 0
	s_nop 0
	s_nop 0
	s_nop 0
	s_nop 0
	s_nop 0
	s_nop 0

; template <class Epi, class Sched, bool ALIGN_EPI = false, bool SP2 = false>
; __device__ __forceinline__ void gemm_phase(PG8_LAS unsigned char* lds, const Gemm g, const Sched& S, const Epi& E, const int tid_arg) {
;     ...
;         const bool has_next = S.next(ui + 1, nxt);
;         const char* nA = has_next ? (const char*)g.A + (size_t)nxt.pm * tstep : cA; const char* nB = has_next ? (const char*)g.Bt + (size_t)nxt.pn * tstep : cB;
;     ...
; #pragma unroll
;         for (int a = 0; a < 2; ++a)
; #pragma unroll
;             for (int b = 0; b < 2; ++b)
; #pragma unroll
;                 for (int m = 0; m < 4; ++m)
; #pragma unroll
;                     for (int n = 0; n < 2; ++n) acc[a][b][m][n] = (f32x4){0.f, 0.f, 0.f, 0.f};
;         cur = nxt; cA = nA; cB = nB; ++ui;
.LBB0_789:
	s_ashr_i32 s27, s26, 31
	s_lshl_b64 s[28:29], s[26:27], 19
	s_add_u32 s28, s40, s28
	s_addc_u32 s29, s41, s29
	s_and_b64 s[30:31], s[10:11], exec
	s_cselect_b32 s27, s29, s35
	s_cselect_b32 s52, s28, s34
	s_ashr_i32 s25, s24, 31
	s_lshl_b64 s[30:31], s[24:25], 19
	s_add_u32 s30, s42, s30
	s_addc_u32 s31, s43, s31
	s_and_b64 s[38:39], s[10:11], exec
	s_cselect_b32 s25, s31, s37
	s_cselect_b32 s53, s30, s36
	s_add_u32 s34, s34, 0x40080
	s_addc_u32 s35, s35, 0
	s_add_u32 s54, s36, 0x100
	v_mov_b32_e32 v4, 0
	s_addc_u32 s55, s37, 0
	s_mov_b32 s56, -2
	v_mov_b32_e32 v5, v4
	v_mov_b32_e32 v6, v4
	v_mov_b32_e32 v7, v4
	v_mov_b32_e32 v8, v4
	v_mov_b32_e32 v9, v4
	v_mov_b32_e32 v10, v4
	v_mov_b32_e32 v11, v4
	v_mov_b32_e32 v20, v4
	v_mov_b32_e32 v21, v4
	v_mov_b32_e32 v22, v4
	v_mov_b32_e32 v23, v4
	v_mov_b32_e32 v24, v4
	v_mov_b32_e32 v25, v4
	v_mov_b32_e32 v26, v4
	v_mov_b32_e32 v27, v4
	v_mov_b32_e32 v36, v4
	v_mov_b32_e32 v37, v4
	v_mov_b32_e32 v38, v4
	v_mov_b32_e32 v39, v4
	v_mov_b32_e32 v40, v4
	v_mov_b32_e32 v41, v4
	v_mov_b32_e32 v42, v4
	v_mov_b32_e32 v43, v4
	v_mov_b32_e32 v52, v4
	v_mov_b32_e32 v53, v4
	v_mov_b32_e32 v54, v4
	v_mov_b32_e32 v55, v4
	v_mov_b32_e32 v56, v4
	v_mov_b32_e32 v57, v4
	v_mov_b32_e32 v58, v4
	v_mov_b32_e32 v59, v4
	v_mov_b32_e32 v12, v4
	v_mov_b32_e32 v13, v4
	v_mov_b32_e32 v14, v4
	v_mov_b32_e32 v15, v4
	v_mov_b32_e32 v16, v4
	v_mov_b32_e32 v17, v4
	v_mov_b32_e32 v18, v4
	v_mov_b32_e32 v19, v4
	v_mov_b32_e32 v28, v4
	v_mov_b32_e32 v29, v4
	v_mov_b32_e32 v30, v4
	v_mov_b32_e32 v31, v4
	v_mov_b32_e32 v32, v4
	v_mov_b32_e32 v33, v4
	v_mov_b32_e32 v34, v4
	v_mov_b32_e32 v35, v4
	v_mov_b32_e32 v44, v4
	v_mov_b32_e32 v45, v4
	v_mov_b32_e32 v46, v4
	v_mov_b32_e32 v47, v4
	v_mov_b32_e32 v48, v4
	v_mov_b32_e32 v49, v4
	v_mov_b32_e32 v50, v4
	v_mov_b32_e32 v51, v4
	v_mov_b32_e32 v60, v4
	v_mov_b32_e32 v61, v4
	v_mov_b32_e32 v62, v4
	v_mov_b32_e32 v63, v4
	v_mov_b32_e32 v64, v4
	v_mov_b32_e32 v65, v4
	v_mov_b32_e32 v66, v4
	v_mov_b32_e32 v67, v4
	v_mov_b32_e32 v68, v4
	v_mov_b32_e32 v69, v4
	v_mov_b32_e32 v70, v4
	v_mov_b32_e32 v71, v4
	v_mov_b32_e32 v72, v4
	v_mov_b32_e32 v73, v4
	v_mov_b32_e32 v74, v4
	v_mov_b32_e32 v75, v4
	v_mov_b32_e32 v84, v4
	v_mov_b32_e32 v85, v4
	v_mov_b32_e32 v86, v4
	v_mov_b32_e32 v87, v4
	v_mov_b32_e32 v88, v4
	v_mov_b32_e32 v89, v4
	v_mov_b32_e32 v90, v4
	v_mov_b32_e32 v91, v4
	v_mov_b32_e32 v100, v4
	v_mov_b32_e32 v101, v4
	v_mov_b32_e32 v102, v4
	v_mov_b32_e32 v103, v4
	v_mov_b32_e32 v104, v4
	v_mov_b32_e32 v105, v4
	v_mov_b32_e32 v106, v4
	v_mov_b32_e32 v107, v4
	v_mov_b32_e32 v116, v4
	v_mov_b32_e32 v117, v4
	v_mov_b32_e32 v118, v4
	v_mov_b32_e32 v119, v4
	s_waitcnt vmcnt(0)
	v_mov_b32_e32 v120, v4
	v_mov_b32_e32 v121, v4
	v_mov_b32_e32 v122, v4
	v_mov_b32_e32 v123, v4
	v_mov_b32_e32 v76, v4
	v_mov_b32_e32 v77, v4
	v_mov_b32_e32 v78, v4
	v_mov_b32_e32 v79, v4
	v_mov_b32_e32 v80, v4
	v_mov_b32_e32 v81, v4
	v_mov_b32_e32 v82, v4
	v_mov_b32_e32 v83, v4
	v_mov_b32_e32 v92, v4
	v_mov_b32_e32 v93, v4
	v_mov_b32_e32 v94, v4
	v_mov_b32_e32 v95, v4
	v_mov_b32_e32 v96, v4
	v_mov_b32_e32 v97, v4
	v_mov_b32_e32 v98, v4
	v_mov_b32_e32 v99, v4
	v_mov_b32_e32 v108, v4
	v_mov_b32_e32 v109, v4
	v_mov_b32_e32 v110, v4
	v_mov_b32_e32 v111, v4
	v_mov_b32_e32 v112, v4
	v_mov_b32_e32 v113, v4
	v_mov_b32_e32 v114, v4
	v_mov_b32_e32 v115, v4
	v_mov_b32_e32 v124, v4
	v_mov_b32_e32 v125, v4
	v_mov_b32_e32 v126, v4
	v_mov_b32_e32 v127, v4
	v_mov_b32_e32 v128, v4
	v_mov_b32_e32 v129, v4
	v_mov_b32_e32 v130, v4
	v_mov_b32_e32 v131, v4
	.p2align 6
	s_nop 0
	s_nop 0
	s_nop 0
	s_nop 0
	s_nop 0
	s_nop 0
	s_nop 0
	s_nop 0
	s_nop 0
	s_nop 0
	s_nop 0
	s_nop 0
	s_nop 0
	s_nop 0

; template <class Epi, class Sched, bool ALIGN_EPI = false, bool SP2 = false>
; __device__ __forceinline__ void gemm_phase(PG8_LAS unsigned char* lds, const Gemm g, const Sched& S, const Epi& E, const int tid_arg) {
;     ...
;         const bool has_next = S.next(ui + 1, nxt);
;         const char* nA = has_next ? (const char*)g.A + (size_t)nxt.pm * tstep : cA; const char* nB = has_next ? (const char*)g.Bt + (size_t)nxt.pn * tstep : cB;
;     ...
; #pragma unroll
;         for (int a = 0; a < 2; ++a)
; #pragma unroll
;             for (int b = 0; b < 2; ++b)
; #pragma unroll
;                 for (int m = 0; m < 4; ++m)
; #pragma unroll
;                     for (int n = 0; n < 2; ++n) acc[a][b][m][n] = (f32x4){0.f, 0.f, 0.f, 0.f};
;         cur = nxt; cA = nA; cB = nB; ++ui;
.LBB0_867:
	s_ashr_i32 s35, s34, 31
	s_lshl_b64 s[36:37], s[34:35], 19
	s_add_u32 s36, s2, s36
	s_addc_u32 s37, s47, s37
	s_and_b64 s[38:39], s[14:15], exec
	s_cselect_b32 s7, s37, s17
	s_cselect_b32 s35, s36, s16
	s_ashr_i32 s31, s30, 31
	s_lshl_b64 s[38:39], s[30:31], 19
	s_add_u32 s38, s48, s38
	s_addc_u32 s39, s49, s39
	s_and_b64 s[44:45], s[14:15], exec
	s_cselect_b32 s31, s39, s43
	s_cselect_b32 s41, s38, s42
	s_add_u32 s16, s16, 0x40080
	s_addc_u32 s17, s17, 0
	s_add_u32 s59, s42, 0x100
	v_mov_b32_e32 v4, 0
	s_addc_u32 s60, s43, 0
	s_mov_b32 s61, -2
	s_waitcnt lgkmcnt(0)
	v_mov_b32_e32 v5, v4
	v_mov_b32_e32 v6, v4
	v_mov_b32_e32 v7, v4
	v_mov_b32_e32 v8, v4
	v_mov_b32_e32 v9, v4
	v_mov_b32_e32 v10, v4
	v_mov_b32_e32 v11, v4
	v_mov_b32_e32 v20, v4
	v_mov_b32_e32 v21, v4
	v_mov_b32_e32 v22, v4
	v_mov_b32_e32 v23, v4
	v_mov_b32_e32 v24, v4
	v_mov_b32_e32 v25, v4
	v_mov_b32_e32 v26, v4
	v_mov_b32_e32 v27, v4
	v_mov_b32_e32 v36, v4
	v_mov_b32_e32 v37, v4
	v_mov_b32_e32 v38, v4
	v_mov_b32_e32 v39, v4
	v_mov_b32_e32 v40, v4
	v_mov_b32_e32 v41, v4
	v_mov_b32_e32 v42, v4
	v_mov_b32_e32 v43, v4
	v_mov_b32_e32 v52, v4
	v_mov_b32_e32 v53, v4
	v_mov_b32_e32 v54, v4
	v_mov_b32_e32 v55, v4
	v_mov_b32_e32 v56, v4
	v_mov_b32_e32 v57, v4
	v_mov_b32_e32 v58, v4
	v_mov_b32_e32 v59, v4
	v_mov_b32_e32 v12, v4
	v_mov_b32_e32 v13, v4
	v_mov_b32_e32 v14, v4
	v_mov_b32_e32 v15, v4
	v_mov_b32_e32 v16, v4
	v_mov_b32_e32 v17, v4
	v_mov_b32_e32 v18, v4
	v_mov_b32_e32 v19, v4
	v_mov_b32_e32 v28, v4
	v_mov_b32_e32 v29, v4
	v_mov_b32_e32 v30, v4
	v_mov_b32_e32 v31, v4
	v_mov_b32_e32 v32, v4
	v_mov_b32_e32 v33, v4
	v_mov_b32_e32 v34, v4
	v_mov_b32_e32 v35, v4
	v_mov_b32_e32 v44, v4
	v_mov_b32_e32 v45, v4
	v_mov_b32_e32 v46, v4
	v_mov_b32_e32 v47, v4
	v_mov_b32_e32 v48, v4
	v_mov_b32_e32 v49, v4
	v_mov_b32_e32 v50, v4
	v_mov_b32_e32 v51, v4
	v_mov_b32_e32 v60, v4
	v_mov_b32_e32 v61, v4
	v_mov_b32_e32 v62, v4
	v_mov_b32_e32 v63, v4
	v_mov_b32_e32 v64, v4
	v_mov_b32_e32 v65, v4
	v_mov_b32_e32 v66, v4
	v_mov_b32_e32 v67, v4
	v_mov_b32_e32 v68, v4
	v_mov_b32_e32 v69, v4
	v_mov_b32_e32 v70, v4
	v_mov_b32_e32 v71, v4
	v_mov_b32_e32 v72, v4
	v_mov_b32_e32 v73, v4
	v_mov_b32_e32 v74, v4
	v_mov_b32_e32 v75, v4
	v_mov_b32_e32 v84, v4
	v_mov_b32_e32 v85, v4
	v_mov_b32_e32 v86, v4
	v_mov_b32_e32 v87, v4
	v_mov_b32_e32 v88, v4
	v_mov_b32_e32 v89, v4
	v_mov_b32_e32 v90, v4
	v_mov_b32_e32 v91, v4
	v_mov_b32_e32 v100, v4
	v_mov_b32_e32 v101, v4
	v_mov_b32_e32 v102, v4
	v_mov_b32_e32 v103, v4
	v_mov_b32_e32 v104, v4
	v_mov_b32_e32 v105, v4
	v_mov_b32_e32 v106, v4
	v_mov_b32_e32 v107, v4
	v_mov_b32_e32 v116, v4
	v_mov_b32_e32 v117, v4
	v_mov_b32_e32 v118, v4
	v_mov_b32_e32 v119, v4
	s_waitcnt vmcnt(0)
	v_mov_b32_e32 v120, v4
	v_mov_b32_e32 v121, v4
	v_mov_b32_e32 v122, v4
	v_mov_b32_e32 v123, v4
	v_mov_b32_e32 v76, v4
	v_mov_b32_e32 v77, v4
	v_mov_b32_e32 v78, v4
	v_mov_b32_e32 v79, v4
	v_mov_b32_e32 v80, v4
	v_mov_b32_e32 v81, v4
	v_mov_b32_e32 v82, v4
	v_mov_b32_e32 v83, v4
	v_mov_b32_e32 v92, v4
	v_mov_b32_e32 v93, v4
	v_mov_b32_e32 v94, v4
	v_mov_b32_e32 v95, v4
	v_mov_b32_e32 v96, v4
	v_mov_b32_e32 v97, v4
	v_mov_b32_e32 v98, v4
	v_mov_b32_e32 v99, v4
	v_mov_b32_e32 v108, v4
	v_mov_b32_e32 v109, v4
	v_mov_b32_e32 v110, v4
	v_mov_b32_e32 v111, v4
	v_mov_b32_e32 v112, v4
	v_mov_b32_e32 v113, v4
	v_mov_b32_e32 v114, v4
	v_mov_b32_e32 v115, v4
	v_mov_b32_e32 v124, v4
	v_mov_b32_e32 v125, v4
	v_mov_b32_e32 v126, v4
	v_mov_b32_e32 v127, v4
	v_mov_b32_e32 v128, v4
	v_mov_b32_e32 v129, v4
	v_mov_b32_e32 v130, v4
	v_mov_b32_e32 v131, v4
	.p2align 6
	s_nop 0
	s_nop 0
	s_nop 0
	s_nop 0
	s_nop 0
	s_nop 0
	s_nop 0
	s_nop 0
	s_nop 0
	s_nop 0
	s_nop 0
	s_nop 0
	s_nop 0
	s_nop 0

; template <class Epi, class Sched, bool ALIGN_EPI = false, bool SP2 = false>
; __device__ __forceinline__ void gemm_phase(PG8_LAS unsigned char* lds, const Gemm g, const Sched& S, const Epi& E, const int tid_arg) {
;     ...
;         const bool has_next = S.next(ui + 1, nxt);
;         const char* nA = has_next ? (const char*)g.A + (size_t)nxt.pm * tstep : cA; const char* nB = has_next ? (const char*)g.Bt + (size_t)nxt.pn * tstep : cB;
;     ...
; #pragma unroll
;         for (int a = 0; a < 2; ++a)
; #pragma unroll
;             for (int b = 0; b < 2; ++b)
; #pragma unroll
;                 for (int m = 0; m < 4; ++m)
; #pragma unroll
;                     for (int n = 0; n < 2; ++n) acc[a][b][m][n] = (f32x4){0.f, 0.f, 0.f, 0.f};
;         cur = nxt; cA = nA; cB = nB; ++ui;
.LBB0_1079:
	s_ashr_i32 s21, s20, 31
	s_lshl_b64 s[22:23], s[20:21], 19
	s_add_u32 s22, s0, s22
	s_addc_u32 s23, s1, s23
	s_and_b64 s[24:25], s[10:11], exec
	s_cselect_b32 s21, s23, s29
	s_cselect_b32 s47, s22, s28
	s_ashr_i32 s17, s16, 31
	s_lshl_b64 s[24:25], s[16:17], 19
	s_add_u32 s24, s2, s24
	s_addc_u32 s25, s3, s25
	s_and_b64 s[34:35], s[10:11], exec
	s_cselect_b32 s17, s25, s31
	s_cselect_b32 s48, s24, s30
	s_add_u32 s28, s28, 0x40080
	s_addc_u32 s29, s29, 0
	s_add_u32 s49, s30, 0x100
	v_mov_b32_e32 v2, 0
	s_addc_u32 s50, s31, 0
	s_mov_b32 s51, -2
	v_mov_b32_e32 v3, v2
	v_mov_b32_e32 v4, v2
	v_mov_b32_e32 v5, v2
	v_mov_b32_e32 v6, v2
	v_mov_b32_e32 v7, v2
	v_mov_b32_e32 v8, v2
	v_mov_b32_e32 v9, v2
	v_mov_b32_e32 v18, v2
	v_mov_b32_e32 v19, v2
	v_mov_b32_e32 v20, v2
	v_mov_b32_e32 v21, v2
	v_mov_b32_e32 v22, v2
	v_mov_b32_e32 v23, v2
	v_mov_b32_e32 v24, v2
	v_mov_b32_e32 v25, v2
	v_mov_b32_e32 v34, v2
	v_mov_b32_e32 v35, v2
	v_mov_b32_e32 v36, v2
	v_mov_b32_e32 v37, v2
	v_mov_b32_e32 v38, v2
	v_mov_b32_e32 v39, v2
	v_mov_b32_e32 v40, v2
	v_mov_b32_e32 v41, v2
	v_mov_b32_e32 v50, v2
	v_mov_b32_e32 v51, v2
	v_mov_b32_e32 v52, v2
	v_mov_b32_e32 v53, v2
	v_mov_b32_e32 v54, v2
	v_mov_b32_e32 v55, v2
	v_mov_b32_e32 v56, v2
	v_mov_b32_e32 v57, v2
	v_mov_b32_e32 v10, v2
	v_mov_b32_e32 v11, v2
	v_mov_b32_e32 v12, v2
	v_mov_b32_e32 v13, v2
	v_mov_b32_e32 v14, v2
	v_mov_b32_e32 v15, v2
	v_mov_b32_e32 v16, v2
	v_mov_b32_e32 v17, v2
	v_mov_b32_e32 v26, v2
	v_mov_b32_e32 v27, v2
	v_mov_b32_e32 v28, v2
	v_mov_b32_e32 v29, v2
	v_mov_b32_e32 v30, v2
	v_mov_b32_e32 v31, v2
	v_mov_b32_e32 v32, v2
	v_mov_b32_e32 v33, v2
	v_mov_b32_e32 v42, v2
	v_mov_b32_e32 v43, v2
	v_mov_b32_e32 v44, v2
	v_mov_b32_e32 v45, v2
	v_mov_b32_e32 v46, v2
	v_mov_b32_e32 v47, v2
	v_mov_b32_e32 v48, v2
	v_mov_b32_e32 v49, v2
	v_mov_b32_e32 v58, v2
	v_mov_b32_e32 v59, v2
	v_mov_b32_e32 v60, v2
	v_mov_b32_e32 v61, v2
	v_mov_b32_e32 v62, v2
	v_mov_b32_e32 v63, v2
	v_mov_b32_e32 v64, v2
	v_mov_b32_e32 v65, v2
	v_mov_b32_e32 v66, v2
	v_mov_b32_e32 v67, v2
	v_mov_b32_e32 v68, v2
	v_mov_b32_e32 v69, v2
	v_mov_b32_e32 v70, v2
	v_mov_b32_e32 v71, v2
	v_mov_b32_e32 v72, v2
	v_mov_b32_e32 v73, v2
	v_mov_b32_e32 v82, v2
	v_mov_b32_e32 v83, v2
	v_mov_b32_e32 v84, v2
	v_mov_b32_e32 v85, v2
	v_mov_b32_e32 v86, v2
	v_mov_b32_e32 v87, v2
	v_mov_b32_e32 v88, v2
	v_mov_b32_e32 v89, v2
	v_mov_b32_e32 v98, v2
	v_mov_b32_e32 v99, v2
	v_mov_b32_e32 v100, v2
	v_mov_b32_e32 v101, v2
	v_mov_b32_e32 v102, v2
	v_mov_b32_e32 v103, v2
	v_mov_b32_e32 v104, v2
	v_mov_b32_e32 v105, v2
	v_mov_b32_e32 v114, v2
	v_mov_b32_e32 v115, v2
	v_mov_b32_e32 v116, v2
	v_mov_b32_e32 v117, v2
	v_mov_b32_e32 v118, v2
	v_mov_b32_e32 v119, v2
	v_mov_b32_e32 v120, v2
	v_mov_b32_e32 v121, v2
	v_mov_b32_e32 v74, v2
	v_mov_b32_e32 v75, v2
	v_mov_b32_e32 v76, v2
	v_mov_b32_e32 v77, v2
	v_mov_b32_e32 v78, v2
	v_mov_b32_e32 v79, v2
	v_mov_b32_e32 v80, v2
	v_mov_b32_e32 v81, v2
	v_mov_b32_e32 v90, v2
	v_mov_b32_e32 v91, v2
	v_mov_b32_e32 v92, v2
	v_mov_b32_e32 v93, v2
	v_mov_b32_e32 v94, v2
	v_mov_b32_e32 v95, v2
	v_mov_b32_e32 v96, v2
	v_mov_b32_e32 v97, v2
	v_mov_b32_e32 v106, v2
	v_mov_b32_e32 v107, v2
	v_mov_b32_e32 v108, v2
	v_mov_b32_e32 v109, v2
	v_mov_b32_e32 v110, v2
	v_mov_b32_e32 v111, v2
	v_mov_b32_e32 v112, v2
	v_mov_b32_e32 v113, v2
	v_mov_b32_e32 v122, v2
	v_mov_b32_e32 v123, v2
	v_mov_b32_e32 v124, v2
	v_mov_b32_e32 v125, v2
	v_mov_b32_e32 v126, v2
	v_mov_b32_e32 v127, v2
	v_mov_b32_e32 v128, v2
	v_mov_b32_e32 v129, v2
	.p2align 6
	s_nop 0
	s_nop 0
	s_nop 0
	s_nop 0

; template <class Epi, class Sched, bool ALIGN_EPI = false, bool SP2 = false>
; __device__ __forceinline__ void gemm_phase(PG8_LAS unsigned char* lds, const Gemm g, const Sched& S, const Epi& E, const int tid_arg) {
;     ...
; #pragma unroll
;         for (int a = 0; a < 2; ++a)
; #pragma unroll
;             for (int b = 0; b < 2; ++b)
; #pragma unroll
;                 for (int m = 0; m < 4; ++m)
; #pragma unroll
;                     for (int n = 0; n < 2; ++n) acc[a][b][m][n] = (f32x4){0.f, 0.f, 0.f, 0.f};
;         cur = nxt; cA = nA; cB = nB; ++ui;
.LBB0_1169:
	s_add_u32 s23, s26, 0x100
	v_mov_b32_e32 v0, 0
	s_addc_u32 s46, s27, 0
	s_mov_b32 s47, -2
	v_mov_b32_e32 v1, v0
	v_mov_b32_e32 v2, v0
	v_mov_b32_e32 v3, v0
	v_mov_b32_e32 v4, v0
	v_mov_b32_e32 v5, v0
	v_mov_b32_e32 v6, v0
	v_mov_b32_e32 v7, v0
	v_mov_b32_e32 v16, v0
	v_mov_b32_e32 v17, v0
	v_mov_b32_e32 v18, v0
	v_mov_b32_e32 v19, v0
	v_mov_b32_e32 v20, v0
	v_mov_b32_e32 v21, v0
	v_mov_b32_e32 v22, v0
	v_mov_b32_e32 v23, v0
	v_mov_b32_e32 v32, v0
	v_mov_b32_e32 v33, v0
	v_mov_b32_e32 v34, v0
	v_mov_b32_e32 v35, v0
	v_mov_b32_e32 v36, v0
	v_mov_b32_e32 v37, v0
	v_mov_b32_e32 v38, v0
	v_mov_b32_e32 v39, v0
	v_mov_b32_e32 v48, v0
	v_mov_b32_e32 v49, v0
	v_mov_b32_e32 v50, v0
	v_mov_b32_e32 v51, v0
	v_mov_b32_e32 v52, v0
	v_mov_b32_e32 v53, v0
	v_mov_b32_e32 v54, v0
	v_mov_b32_e32 v55, v0
	v_mov_b32_e32 v8, v0
	v_mov_b32_e32 v9, v0
	v_mov_b32_e32 v10, v0
	v_mov_b32_e32 v11, v0
	v_mov_b32_e32 v12, v0
	v_mov_b32_e32 v13, v0
	v_mov_b32_e32 v14, v0
	v_mov_b32_e32 v15, v0
	v_mov_b32_e32 v24, v0
	v_mov_b32_e32 v25, v0
	v_mov_b32_e32 v26, v0
	v_mov_b32_e32 v27, v0
	v_mov_b32_e32 v28, v0
	v_mov_b32_e32 v29, v0
	v_mov_b32_e32 v30, v0
	v_mov_b32_e32 v31, v0
	v_mov_b32_e32 v40, v0
	v_mov_b32_e32 v41, v0
	v_mov_b32_e32 v42, v0
	v_mov_b32_e32 v43, v0
	v_mov_b32_e32 v44, v0
	v_mov_b32_e32 v45, v0
	v_mov_b32_e32 v46, v0
	v_mov_b32_e32 v47, v0
	v_mov_b32_e32 v56, v0
	v_mov_b32_e32 v57, v0
	v_mov_b32_e32 v58, v0
	v_mov_b32_e32 v59, v0
	v_mov_b32_e32 v60, v0
	v_mov_b32_e32 v61, v0
	v_mov_b32_e32 v62, v0
	v_mov_b32_e32 v63, v0
	v_mov_b32_e32 v64, v0
	v_mov_b32_e32 v65, v0
	v_mov_b32_e32 v66, v0
	v_mov_b32_e32 v67, v0
	v_mov_b32_e32 v68, v0
	v_mov_b32_e32 v69, v0
	v_mov_b32_e32 v70, v0
	v_mov_b32_e32 v71, v0
	v_mov_b32_e32 v80, v0
	v_mov_b32_e32 v81, v0
	v_mov_b32_e32 v82, v0
	v_mov_b32_e32 v83, v0
	v_mov_b32_e32 v84, v0
	v_mov_b32_e32 v85, v0
	v_mov_b32_e32 v86, v0
	v_mov_b32_e32 v87, v0
	v_mov_b32_e32 v96, v0
	v_mov_b32_e32 v97, v0
	v_mov_b32_e32 v98, v0
	v_mov_b32_e32 v99, v0
	v_mov_b32_e32 v100, v0
	v_mov_b32_e32 v101, v0
	v_mov_b32_e32 v102, v0
	v_mov_b32_e32 v103, v0
	v_mov_b32_e32 v112, v0
	v_mov_b32_e32 v113, v0
	v_mov_b32_e32 v114, v0
	v_mov_b32_e32 v115, v0
	v_mov_b32_e32 v116, v0
	v_mov_b32_e32 v117, v0
	v_mov_b32_e32 v118, v0
	v_mov_b32_e32 v119, v0
	v_mov_b32_e32 v72, v0
	v_mov_b32_e32 v73, v0
	v_mov_b32_e32 v74, v0
	v_mov_b32_e32 v75, v0
	v_mov_b32_e32 v76, v0
	v_mov_b32_e32 v77, v0
	v_mov_b32_e32 v78, v0
	v_mov_b32_e32 v79, v0
	v_mov_b32_e32 v88, v0
	v_mov_b32_e32 v89, v0
	v_mov_b32_e32 v90, v0
	v_mov_b32_e32 v91, v0
	v_mov_b32_e32 v92, v0
	v_mov_b32_e32 v93, v0
	v_mov_b32_e32 v94, v0
	v_mov_b32_e32 v95, v0
	v_mov_b32_e32 v104, v0
	v_mov_b32_e32 v105, v0
	v_mov_b32_e32 v106, v0
	v_mov_b32_e32 v107, v0
	v_mov_b32_e32 v108, v0
	v_mov_b32_e32 v109, v0
	v_mov_b32_e32 v110, v0
	v_mov_b32_e32 v111, v0
	v_mov_b32_e32 v120, v0
	v_mov_b32_e32 v121, v0
	v_mov_b32_e32 v122, v0
	v_mov_b32_e32 v123, v0
	v_mov_b32_e32 v124, v0
	v_mov_b32_e32 v125, v0
	v_mov_b32_e32 v126, v0
	v_mov_b32_e32 v127, v0
	.p2align 6
	s_nop 0
	s_nop 0
	s_nop 0
	s_nop 0
